# GEMM accumulators cleared with v_pk_mov_b32 register pairs (half the clearing instructions per unit)
# baseline (speedup 1.0000x reference)
.LBB0_336:
	s_ashr_i32 s31, s30, 31
	s_lshl_b64 s[34:35], s[30:31], 20
	s_add_u32 s34, s44, s34
	s_addc_u32 s35, s45, s35
	s_and_b64 s[36:37], s[10:11], exec
	s_cselect_b32 s31, s35, s51
	s_cselect_b32 s47, s34, s50
	s_ashr_i32 s27, s26, 31
	s_lshl_b64 s[36:37], s[26:27], 20
	s_add_u32 s36, s54, s36
	s_addc_u32 s37, s55, s37
	s_and_b64 s[52:53], s[10:11], exec
	s_cselect_b32 s27, s37, s49
	s_cselect_b32 s71, s36, s48
	s_add_u32 s72, s48, 0x100
	s_addc_u32 s74, s49, 0
	s_add_u32 s48, s50, 0x80080
	v_mov_b32_e32 v0, 0
	s_addc_u32 s49, s51, 0
	s_mov_b32 s75, -2
	s_waitcnt lgkmcnt(0)
	v_mov_b32_e32 v1, v0
	v_pk_mov_b32 v[2:3], 0, 0
	v_pk_mov_b32 v[4:5], 0, 0
	v_pk_mov_b32 v[6:7], 0, 0
	v_pk_mov_b32 v[16:17], 0, 0
	v_pk_mov_b32 v[18:19], 0, 0
	v_pk_mov_b32 v[20:21], 0, 0
	v_pk_mov_b32 v[22:23], 0, 0
	v_pk_mov_b32 v[32:33], 0, 0
	v_pk_mov_b32 v[34:35], 0, 0
	v_pk_mov_b32 v[36:37], 0, 0
	v_pk_mov_b32 v[38:39], 0, 0
	v_pk_mov_b32 v[48:49], 0, 0
	v_pk_mov_b32 v[50:51], 0, 0
	v_pk_mov_b32 v[52:53], 0, 0
	v_pk_mov_b32 v[54:55], 0, 0
	v_pk_mov_b32 v[8:9], 0, 0
	v_pk_mov_b32 v[10:11], 0, 0
	v_pk_mov_b32 v[12:13], 0, 0
	v_pk_mov_b32 v[14:15], 0, 0
	v_pk_mov_b32 v[24:25], 0, 0
	v_pk_mov_b32 v[26:27], 0, 0
	v_pk_mov_b32 v[28:29], 0, 0
	v_pk_mov_b32 v[30:31], 0, 0
	v_pk_mov_b32 v[40:41], 0, 0
	v_pk_mov_b32 v[42:43], 0, 0
	v_pk_mov_b32 v[44:45], 0, 0
	v_pk_mov_b32 v[46:47], 0, 0
	v_pk_mov_b32 v[56:57], 0, 0
	v_pk_mov_b32 v[58:59], 0, 0
	v_pk_mov_b32 v[60:61], 0, 0
	v_pk_mov_b32 v[62:63], 0, 0
	v_pk_mov_b32 v[64:65], 0, 0
	v_pk_mov_b32 v[66:67], 0, 0
	v_pk_mov_b32 v[68:69], 0, 0
	v_pk_mov_b32 v[70:71], 0, 0
	v_pk_mov_b32 v[80:81], 0, 0
	v_pk_mov_b32 v[82:83], 0, 0
	v_pk_mov_b32 v[84:85], 0, 0
	v_pk_mov_b32 v[86:87], 0, 0
	v_pk_mov_b32 v[96:97], 0, 0
	v_pk_mov_b32 v[98:99], 0, 0
	v_pk_mov_b32 v[100:101], 0, 0
	v_pk_mov_b32 v[102:103], 0, 0
	v_pk_mov_b32 v[112:113], 0, 0
	v_pk_mov_b32 v[114:115], 0, 0
	v_pk_mov_b32 v[116:117], 0, 0
	v_pk_mov_b32 v[118:119], 0, 0
	v_pk_mov_b32 v[72:73], 0, 0
	v_pk_mov_b32 v[74:75], 0, 0
	v_pk_mov_b32 v[76:77], 0, 0
	v_pk_mov_b32 v[78:79], 0, 0
	v_pk_mov_b32 v[88:89], 0, 0
	v_pk_mov_b32 v[90:91], 0, 0
	v_pk_mov_b32 v[92:93], 0, 0
	v_pk_mov_b32 v[94:95], 0, 0
	v_pk_mov_b32 v[104:105], 0, 0
	v_pk_mov_b32 v[106:107], 0, 0
	v_pk_mov_b32 v[108:109], 0, 0
	v_pk_mov_b32 v[110:111], 0, 0
	v_pk_mov_b32 v[120:121], 0, 0
	v_pk_mov_b32 v[122:123], 0, 0
	v_pk_mov_b32 v[124:125], 0, 0
	v_pk_mov_b32 v[126:127], 0, 0

.LBB0_522:
	s_add_u32 s46, s36, 0x100
	v_mov_b32_e32 v0, 0
	s_addc_u32 s47, s37, 0
	s_mov_b32 s66, -2
	s_waitcnt lgkmcnt(0)
	v_mov_b32_e32 v1, v0
	v_pk_mov_b32 v[2:3], 0, 0
	v_pk_mov_b32 v[4:5], 0, 0
	v_pk_mov_b32 v[6:7], 0, 0
	v_pk_mov_b32 v[16:17], 0, 0
	v_pk_mov_b32 v[18:19], 0, 0
	v_pk_mov_b32 v[20:21], 0, 0
	v_pk_mov_b32 v[22:23], 0, 0
	v_pk_mov_b32 v[32:33], 0, 0
	v_pk_mov_b32 v[34:35], 0, 0
	v_pk_mov_b32 v[36:37], 0, 0
	v_pk_mov_b32 v[38:39], 0, 0
	v_pk_mov_b32 v[48:49], 0, 0
	v_pk_mov_b32 v[50:51], 0, 0
	v_pk_mov_b32 v[52:53], 0, 0
	v_pk_mov_b32 v[54:55], 0, 0
	v_pk_mov_b32 v[8:9], 0, 0
	v_pk_mov_b32 v[10:11], 0, 0
	v_pk_mov_b32 v[12:13], 0, 0
	v_pk_mov_b32 v[14:15], 0, 0
	v_pk_mov_b32 v[24:25], 0, 0
	v_pk_mov_b32 v[26:27], 0, 0
	v_pk_mov_b32 v[28:29], 0, 0
	v_pk_mov_b32 v[30:31], 0, 0
	v_pk_mov_b32 v[40:41], 0, 0
	v_pk_mov_b32 v[42:43], 0, 0
	v_pk_mov_b32 v[44:45], 0, 0
	v_pk_mov_b32 v[46:47], 0, 0
	v_pk_mov_b32 v[56:57], 0, 0
	v_pk_mov_b32 v[58:59], 0, 0
	v_pk_mov_b32 v[60:61], 0, 0
	v_pk_mov_b32 v[62:63], 0, 0
	v_pk_mov_b32 v[64:65], 0, 0
	v_pk_mov_b32 v[66:67], 0, 0
	v_pk_mov_b32 v[68:69], 0, 0
	v_pk_mov_b32 v[70:71], 0, 0
	v_pk_mov_b32 v[80:81], 0, 0
	v_pk_mov_b32 v[82:83], 0, 0
	v_pk_mov_b32 v[84:85], 0, 0
	v_pk_mov_b32 v[86:87], 0, 0
	v_pk_mov_b32 v[96:97], 0, 0
	v_pk_mov_b32 v[98:99], 0, 0
	v_pk_mov_b32 v[100:101], 0, 0
	v_pk_mov_b32 v[102:103], 0, 0
	v_pk_mov_b32 v[112:113], 0, 0
	v_pk_mov_b32 v[114:115], 0, 0
	v_pk_mov_b32 v[116:117], 0, 0
	v_pk_mov_b32 v[118:119], 0, 0
	v_pk_mov_b32 v[72:73], 0, 0
	v_pk_mov_b32 v[74:75], 0, 0
	v_pk_mov_b32 v[76:77], 0, 0
	v_pk_mov_b32 v[78:79], 0, 0
	v_pk_mov_b32 v[88:89], 0, 0
	v_pk_mov_b32 v[90:91], 0, 0
	v_pk_mov_b32 v[92:93], 0, 0
	v_pk_mov_b32 v[94:95], 0, 0
	v_pk_mov_b32 v[104:105], 0, 0
	v_pk_mov_b32 v[106:107], 0, 0
	v_pk_mov_b32 v[108:109], 0, 0
	v_pk_mov_b32 v[110:111], 0, 0
	v_pk_mov_b32 v[120:121], 0, 0
	v_pk_mov_b32 v[122:123], 0, 0
	v_pk_mov_b32 v[124:125], 0, 0
	v_pk_mov_b32 v[126:127], 0, 0

.LBB0_616:
	s_ashr_i32 s35, s34, 31
	s_lshl_b64 s[36:37], s[34:35], 20
	s_add_u32 s36, s12, s36
	s_addc_u32 s37, s13, s37
	s_and_b64 s[46:47], s[10:11], exec
	s_cselect_b32 s35, s37, s59
	s_cselect_b32 s46, s36, s58
	s_ashr_i32 s31, s30, 31
	s_lshl_b64 s[50:51], s[30:31], 20
	s_add_u32 s52, s6, s50
	s_addc_u32 s53, s7, s51
	s_and_b64 s[50:51], s[10:11], exec
	s_cselect_b32 s31, s53, s57
	s_cselect_b32 s47, s52, s56
	s_add_u32 s50, s56, 0x100
	s_addc_u32 s51, s57, 0
	s_add_u32 s56, s58, 0x80080
	v_mov_b32_e32 v0, 0
	s_addc_u32 s57, s59, 0
	s_mov_b32 s55, -2
	s_waitcnt lgkmcnt(0)
	v_mov_b32_e32 v1, v0
	v_pk_mov_b32 v[2:3], 0, 0
	v_pk_mov_b32 v[4:5], 0, 0
	v_pk_mov_b32 v[6:7], 0, 0
	v_pk_mov_b32 v[16:17], 0, 0
	v_pk_mov_b32 v[18:19], 0, 0
	v_pk_mov_b32 v[20:21], 0, 0
	v_pk_mov_b32 v[22:23], 0, 0
	v_pk_mov_b32 v[32:33], 0, 0
	v_pk_mov_b32 v[34:35], 0, 0
	v_pk_mov_b32 v[36:37], 0, 0
	v_pk_mov_b32 v[38:39], 0, 0
	v_pk_mov_b32 v[48:49], 0, 0
	v_pk_mov_b32 v[50:51], 0, 0
	v_pk_mov_b32 v[52:53], 0, 0
	v_pk_mov_b32 v[54:55], 0, 0
	v_pk_mov_b32 v[8:9], 0, 0
	v_pk_mov_b32 v[10:11], 0, 0
	v_pk_mov_b32 v[12:13], 0, 0
	v_pk_mov_b32 v[14:15], 0, 0
	v_pk_mov_b32 v[24:25], 0, 0
	v_pk_mov_b32 v[26:27], 0, 0
	v_pk_mov_b32 v[28:29], 0, 0
	v_pk_mov_b32 v[30:31], 0, 0
	v_pk_mov_b32 v[40:41], 0, 0
	v_pk_mov_b32 v[42:43], 0, 0
	v_pk_mov_b32 v[44:45], 0, 0
	v_pk_mov_b32 v[46:47], 0, 0
	v_pk_mov_b32 v[56:57], 0, 0
	v_pk_mov_b32 v[58:59], 0, 0
	v_pk_mov_b32 v[60:61], 0, 0
	v_pk_mov_b32 v[62:63], 0, 0
	v_pk_mov_b32 v[64:65], 0, 0
	v_pk_mov_b32 v[66:67], 0, 0
	v_pk_mov_b32 v[68:69], 0, 0
	v_pk_mov_b32 v[70:71], 0, 0
	v_pk_mov_b32 v[80:81], 0, 0
	v_pk_mov_b32 v[82:83], 0, 0
	v_pk_mov_b32 v[84:85], 0, 0
	v_pk_mov_b32 v[86:87], 0, 0
	v_pk_mov_b32 v[96:97], 0, 0
	v_pk_mov_b32 v[98:99], 0, 0
	v_pk_mov_b32 v[100:101], 0, 0
	v_pk_mov_b32 v[102:103], 0, 0
	v_pk_mov_b32 v[112:113], 0, 0
	v_pk_mov_b32 v[114:115], 0, 0
	v_pk_mov_b32 v[116:117], 0, 0
	v_pk_mov_b32 v[118:119], 0, 0
	v_pk_mov_b32 v[72:73], 0, 0
	v_pk_mov_b32 v[74:75], 0, 0
	v_pk_mov_b32 v[76:77], 0, 0
	v_pk_mov_b32 v[78:79], 0, 0
	v_pk_mov_b32 v[88:89], 0, 0
	v_pk_mov_b32 v[90:91], 0, 0
	v_pk_mov_b32 v[92:93], 0, 0
	v_pk_mov_b32 v[94:95], 0, 0
	v_pk_mov_b32 v[104:105], 0, 0
	v_pk_mov_b32 v[106:107], 0, 0
	v_pk_mov_b32 v[108:109], 0, 0
	v_pk_mov_b32 v[110:111], 0, 0
	v_pk_mov_b32 v[120:121], 0, 0
	v_pk_mov_b32 v[122:123], 0, 0
	v_pk_mov_b32 v[124:125], 0, 0
	v_pk_mov_b32 v[126:127], 0, 0

.LBB0_730:
	s_ashr_i32 s21, s20, 31
	s_lshl_b64 s[22:23], s[20:21], 20
	s_add_u32 s22, s6, s22
	s_addc_u32 s23, s7, s23
	s_and_b64 s[24:25], s[8:9], exec
	s_cselect_b32 s21, s23, s35
	s_cselect_b32 s46, s22, s34
	s_ashr_i32 s19, s18, 31
	s_lshl_b64 s[24:25], s[18:19], 20
	s_add_u32 s24, s44, s24
	s_addc_u32 s25, s45, s25
	s_and_b64 s[36:37], s[8:9], exec
	s_cselect_b32 s19, s25, s31
	s_cselect_b32 s47, s24, s30
	s_add_u32 s59, s30, 0x100
	s_addc_u32 s60, s31, 0
	s_add_u32 s30, s34, 0x80080
	v_mov_b32_e32 v0, 0
	s_addc_u32 s31, s35, 0
	s_mov_b32 s61, -2
	v_mov_b32_e32 v1, v0
	v_pk_mov_b32 v[2:3], 0, 0
	v_pk_mov_b32 v[4:5], 0, 0
	v_pk_mov_b32 v[6:7], 0, 0
	v_pk_mov_b32 v[16:17], 0, 0
	v_pk_mov_b32 v[18:19], 0, 0
	v_pk_mov_b32 v[20:21], 0, 0
	v_pk_mov_b32 v[22:23], 0, 0
	v_pk_mov_b32 v[32:33], 0, 0
	v_pk_mov_b32 v[34:35], 0, 0
	v_pk_mov_b32 v[36:37], 0, 0
	v_pk_mov_b32 v[38:39], 0, 0
	v_pk_mov_b32 v[48:49], 0, 0
	v_pk_mov_b32 v[50:51], 0, 0
	v_pk_mov_b32 v[52:53], 0, 0
	v_pk_mov_b32 v[54:55], 0, 0
	v_pk_mov_b32 v[8:9], 0, 0
	v_pk_mov_b32 v[10:11], 0, 0
	v_pk_mov_b32 v[12:13], 0, 0
	v_pk_mov_b32 v[14:15], 0, 0
	v_pk_mov_b32 v[24:25], 0, 0
	v_pk_mov_b32 v[26:27], 0, 0
	v_pk_mov_b32 v[28:29], 0, 0
	v_pk_mov_b32 v[30:31], 0, 0
	v_pk_mov_b32 v[40:41], 0, 0
	v_pk_mov_b32 v[42:43], 0, 0
	v_pk_mov_b32 v[44:45], 0, 0
	v_pk_mov_b32 v[46:47], 0, 0
	v_pk_mov_b32 v[56:57], 0, 0
	v_pk_mov_b32 v[58:59], 0, 0
	v_pk_mov_b32 v[60:61], 0, 0
	v_pk_mov_b32 v[62:63], 0, 0
	v_pk_mov_b32 v[64:65], 0, 0
	v_pk_mov_b32 v[66:67], 0, 0
	v_pk_mov_b32 v[68:69], 0, 0
	v_pk_mov_b32 v[70:71], 0, 0
	v_pk_mov_b32 v[80:81], 0, 0
	v_pk_mov_b32 v[82:83], 0, 0
	v_pk_mov_b32 v[84:85], 0, 0
	v_pk_mov_b32 v[86:87], 0, 0
	v_pk_mov_b32 v[96:97], 0, 0
	v_pk_mov_b32 v[98:99], 0, 0
	v_pk_mov_b32 v[100:101], 0, 0
	v_pk_mov_b32 v[102:103], 0, 0
	v_pk_mov_b32 v[112:113], 0, 0
	v_pk_mov_b32 v[114:115], 0, 0
	v_pk_mov_b32 v[116:117], 0, 0
	v_pk_mov_b32 v[118:119], 0, 0
	v_pk_mov_b32 v[72:73], 0, 0
	v_pk_mov_b32 v[74:75], 0, 0
	v_pk_mov_b32 v[76:77], 0, 0
	v_pk_mov_b32 v[78:79], 0, 0
	v_pk_mov_b32 v[88:89], 0, 0
	v_pk_mov_b32 v[90:91], 0, 0
	v_pk_mov_b32 v[92:93], 0, 0
	v_pk_mov_b32 v[94:95], 0, 0
	v_pk_mov_b32 v[104:105], 0, 0
	v_pk_mov_b32 v[106:107], 0, 0
	v_pk_mov_b32 v[108:109], 0, 0
	v_pk_mov_b32 v[110:111], 0, 0
	v_pk_mov_b32 v[120:121], 0, 0
	v_pk_mov_b32 v[122:123], 0, 0
	v_pk_mov_b32 v[124:125], 0, 0
	v_pk_mov_b32 v[126:127], 0, 0

.LBB0_1136:
	s_add_u32 s46, s34, 0x100
	v_mov_b32_e32 v0, 0
	s_addc_u32 s47, s35, 0
	s_mov_b32 s66, -2
	s_waitcnt lgkmcnt(0)
	v_mov_b32_e32 v1, v0
	v_pk_mov_b32 v[2:3], 0, 0
	v_pk_mov_b32 v[4:5], 0, 0
	v_pk_mov_b32 v[6:7], 0, 0
	v_pk_mov_b32 v[16:17], 0, 0
	v_pk_mov_b32 v[18:19], 0, 0
	v_pk_mov_b32 v[20:21], 0, 0
	v_pk_mov_b32 v[22:23], 0, 0
	v_pk_mov_b32 v[32:33], 0, 0
	v_pk_mov_b32 v[34:35], 0, 0
	v_pk_mov_b32 v[36:37], 0, 0
	v_pk_mov_b32 v[38:39], 0, 0
	v_pk_mov_b32 v[48:49], 0, 0
	v_pk_mov_b32 v[50:51], 0, 0
	v_pk_mov_b32 v[52:53], 0, 0
	v_pk_mov_b32 v[54:55], 0, 0
	v_pk_mov_b32 v[8:9], 0, 0
	v_pk_mov_b32 v[10:11], 0, 0
	v_pk_mov_b32 v[12:13], 0, 0
	v_pk_mov_b32 v[14:15], 0, 0
	v_pk_mov_b32 v[24:25], 0, 0
	v_pk_mov_b32 v[26:27], 0, 0
	v_pk_mov_b32 v[28:29], 0, 0
	v_pk_mov_b32 v[30:31], 0, 0
	v_pk_mov_b32 v[40:41], 0, 0
	v_pk_mov_b32 v[42:43], 0, 0
	v_pk_mov_b32 v[44:45], 0, 0
	v_pk_mov_b32 v[46:47], 0, 0
	s_waitcnt vmcnt(0)
	v_mov_b32_e32 v56, v0
	v_mov_b32_e32 v57, v0
	v_mov_b32_e32 v58, v0
	v_mov_b32_e32 v59, v0
	v_mov_b32_e32 v60, v0
	v_mov_b32_e32 v61, v0
	v_mov_b32_e32 v62, v0
	v_mov_b32_e32 v63, v0
	v_mov_b32_e32 v64, v0
	v_mov_b32_e32 v65, v0
	v_mov_b32_e32 v66, v0
	v_mov_b32_e32 v67, v0
	v_mov_b32_e32 v68, v0
	v_mov_b32_e32 v69, v0
	v_mov_b32_e32 v70, v0
	v_mov_b32_e32 v71, v0
	v_mov_b32_e32 v80, v0
	v_mov_b32_e32 v81, v0
	v_mov_b32_e32 v82, v0
	v_mov_b32_e32 v83, v0
	v_mov_b32_e32 v84, v0
	v_mov_b32_e32 v85, v0
	v_mov_b32_e32 v86, v0
	v_mov_b32_e32 v87, v0
	v_mov_b32_e32 v96, v0
	v_mov_b32_e32 v97, v0
	v_mov_b32_e32 v98, v0
	v_mov_b32_e32 v99, v0
	v_mov_b32_e32 v100, v0
	v_mov_b32_e32 v101, v0
	v_mov_b32_e32 v102, v0
	v_mov_b32_e32 v103, v0
	v_mov_b32_e32 v112, v0
	v_mov_b32_e32 v113, v0
	v_mov_b32_e32 v114, v0
	v_mov_b32_e32 v115, v0
	v_mov_b32_e32 v116, v0
	v_mov_b32_e32 v117, v0
	v_mov_b32_e32 v118, v0
	v_mov_b32_e32 v119, v0
	v_mov_b32_e32 v72, v0
	v_mov_b32_e32 v73, v0
	v_mov_b32_e32 v74, v0
	v_mov_b32_e32 v75, v0
	v_mov_b32_e32 v76, v0
	v_mov_b32_e32 v77, v0
	v_mov_b32_e32 v78, v0
	v_mov_b32_e32 v79, v0
	v_mov_b32_e32 v88, v0
	v_mov_b32_e32 v89, v0
	v_mov_b32_e32 v90, v0
	v_mov_b32_e32 v91, v0
	v_mov_b32_e32 v92, v0
	v_mov_b32_e32 v93, v0
	v_mov_b32_e32 v94, v0
	v_mov_b32_e32 v95, v0
	v_mov_b32_e32 v104, v0
	v_mov_b32_e32 v105, v0
	v_mov_b32_e32 v106, v0
	v_mov_b32_e32 v107, v0
	v_mov_b32_e32 v108, v0
	v_mov_b32_e32 v109, v0
	v_mov_b32_e32 v110, v0
	v_mov_b32_e32 v111, v0
	v_mov_b32_e32 v120, v0
	v_mov_b32_e32 v121, v0
	v_mov_b32_e32 v122, v0
	v_mov_b32_e32 v123, v0
	v_mov_b32_e32 v124, v0
	v_mov_b32_e32 v125, v0
	v_mov_b32_e32 v126, v0
	v_mov_b32_e32 v127, v0

.LBB0_1227:
	v_add_u32_e32 v164, s56, v150
	v_add_u32_e32 v180, s57, v150
	s_add_u32 s34, s16, s30
	ds_read_b128 v[152:155], v164
	ds_read_b128 v[156:159], v164 offset:1024
	ds_read_b128 v[160:163], v164 offset:2048
	ds_read_b128 v[164:167], v164 offset:3072
	ds_read_b128 v[168:171], v180
	ds_read_b128 v[172:175], v180 offset:1024
	ds_read_b128 v[176:179], v180 offset:2048
	ds_read_b128 v[180:183], v180 offset:3072
	s_addc_u32 s35, s17, s31
	s_add_u32 s34, s34, 0x100
	s_addc_u32 s35, s35, 0
	s_add_u32 s64, s59, s30
	s_addc_u32 s65, s60, s31
	s_cmpk_eq_i32 s30, 0xf00
	s_cselect_b32 s37, s23, s35
	s_cselect_b32 s36, s61, s34
	s_cselect_b32 s35, s21, s65
	s_cselect_b32 s34, s62, s64
	v_lshl_add_u64 v[216:217], v[146:147], 0, s[30:31]
	s_add_i32 m0, s48, 0xc000
	ds_read_b128 v[184:187], v151
	ds_read_b128 v[188:191], v151 offset:1024
	ds_read_b128 v[192:195], v151 offset:2048
	ds_read_b128 v[196:199], v151 offset:3072
	ds_read_b128 v[200:203], v151 offset:4096
	ds_read_b128 v[204:207], v151 offset:5120
	ds_read_b128 v[208:211], v151 offset:6144
	ds_read_b128 v[212:215], v151 offset:7168
	global_load_lds_dwordx4 v[216:217], off
	v_lshl_add_u64 v[216:217], v[144:145], 0, s[30:31]
	s_add_i32 m0, s48, 0xe000
	s_nop 0
	global_load_lds_dwordx4 v[216:217], off
	s_waitcnt vmcnt(8)
	s_waitcnt lgkmcnt(0)
	s_barrier
	s_setprio 1
	v_mfma_f32_16x16x32_bf16 v[124:127], v[152:155], v[184:187], v[124:127]
	v_mfma_f32_16x16x32_bf16 v[120:123], v[160:163], v[184:187], v[120:123]
	v_mfma_f32_16x16x32_bf16 v[108:111], v[152:155], v[192:195], v[108:111]
	v_mfma_f32_16x16x32_bf16 v[104:107], v[160:163], v[192:195], v[104:107]
	v_mfma_f32_16x16x32_bf16 v[92:95], v[152:155], v[200:203], v[92:95]
	v_mfma_f32_16x16x32_bf16 v[88:91], v[160:163], v[200:203], v[88:91]
	v_mfma_f32_16x16x32_bf16 v[76:79], v[152:155], v[208:211], v[76:79]
	v_mfma_f32_16x16x32_bf16 v[72:75], v[160:163], v[208:211], v[72:75]
	v_mfma_f32_16x16x32_bf16 v[124:127], v[156:159], v[188:191], v[124:127]
	v_mfma_f32_16x16x32_bf16 v[120:123], v[164:167], v[188:191], v[120:123]
	v_mfma_f32_16x16x32_bf16 v[108:111], v[156:159], v[196:199], v[108:111]
	v_mfma_f32_16x16x32_bf16 v[104:107], v[164:167], v[196:199], v[104:107]
	v_mfma_f32_16x16x32_bf16 v[92:95], v[156:159], v[204:207], v[92:95]
	v_mfma_f32_16x16x32_bf16 v[88:91], v[164:167], v[204:207], v[88:91]
	v_mfma_f32_16x16x32_bf16 v[76:79], v[156:159], v[212:215], v[76:79]
	v_mfma_f32_16x16x32_bf16 v[72:75], v[164:167], v[212:215], v[72:75]
	v_mfma_f32_16x16x32_bf16 v[116:119], v[168:171], v[184:187], v[116:119]
	v_mfma_f32_16x16x32_bf16 v[112:115], v[176:179], v[184:187], v[112:115]
	v_mfma_f32_16x16x32_bf16 v[100:103], v[168:171], v[192:195], v[100:103]
	v_mfma_f32_16x16x32_bf16 v[96:99], v[176:179], v[192:195], v[96:99]
	v_mfma_f32_16x16x32_bf16 v[84:87], v[168:171], v[200:203], v[84:87]
	v_mfma_f32_16x16x32_bf16 v[80:83], v[176:179], v[200:203], v[80:83]
	v_mfma_f32_16x16x32_bf16 v[68:71], v[168:171], v[208:211], v[68:71]
	v_mfma_f32_16x16x32_bf16 v[64:67], v[176:179], v[208:211], v[64:67]
	v_mfma_f32_16x16x32_bf16 v[116:119], v[172:175], v[188:191], v[116:119]
	v_mfma_f32_16x16x32_bf16 v[112:115], v[180:183], v[188:191], v[112:115]
	v_mfma_f32_16x16x32_bf16 v[100:103], v[172:175], v[196:199], v[100:103]
	v_mfma_f32_16x16x32_bf16 v[96:99], v[180:183], v[196:199], v[96:99]
	v_mfma_f32_16x16x32_bf16 v[84:87], v[172:175], v[204:207], v[84:87]
	v_mfma_f32_16x16x32_bf16 v[80:83], v[180:183], v[204:207], v[80:83]
	v_mfma_f32_16x16x32_bf16 v[68:71], v[172:175], v[212:215], v[68:71]
	v_mfma_f32_16x16x32_bf16 v[64:67], v[180:183], v[212:215], v[64:67]
	s_setprio 0
	s_barrier
	s_add_i32 s64, s56, s47
	v_lshl_add_u64 v[216:217], s[34:35], 0, v[130:131]
	s_mov_b32 m0, s64
	ds_read_b128 v[184:187], v151 offset:16384
	ds_read_b128 v[188:191], v151 offset:17408
	ds_read_b128 v[192:195], v151 offset:18432
	ds_read_b128 v[196:199], v151 offset:19456
	ds_read_b128 v[200:203], v151 offset:20480
	ds_read_b128 v[204:207], v151 offset:21504
	ds_read_b128 v[208:211], v151 offset:22528
	ds_read_b128 v[212:215], v151 offset:23552
	global_load_lds_dwordx4 v[216:217], off
	s_add_i32 m0, s64, 0x2000
	s_add_u32 s64, s34, 0x80000
	v_lshl_add_u64 v[218:219], s[34:35], 0, v[134:135]
	s_addc_u32 s65, s35, 0
	s_add_i32 s66, s57, s47
	global_load_lds_dwordx4 v[218:219], off
	v_lshl_add_u64 v[220:221], s[64:65], 0, v[130:131]
	s_mov_b32 m0, s66
	v_lshl_add_u64 v[222:223], s[36:37], 0, v[132:133]
	global_load_lds_dwordx4 v[220:221], off
	v_lshl_add_u64 v[220:221], s[64:65], 0, v[134:135]
	s_add_i32 m0, s66, 0x2000
	s_nop 0
	global_load_lds_dwordx4 v[220:221], off
	v_lshl_add_u64 v[220:221], s[36:37], 0, v[128:129]
	s_mov_b32 m0, s48
	s_nop 0
	global_load_lds_dwordx4 v[220:221], off
	s_mov_b32 m0, s49
	s_nop 0
	global_load_lds_dwordx4 v[222:223], off
	s_waitcnt vmcnt(8)
	s_waitcnt lgkmcnt(0)
	s_barrier
	s_setprio 1
	v_mfma_f32_16x16x32_bf16 v[60:63], v[152:155], v[184:187], v[60:63]
	v_mfma_f32_16x16x32_bf16 v[56:59], v[160:163], v[184:187], v[56:59]
	v_mfma_f32_16x16x32_bf16 v[44:47], v[152:155], v[192:195], v[44:47]
	v_mfma_f32_16x16x32_bf16 v[40:43], v[160:163], v[192:195], v[40:43]
	v_mfma_f32_16x16x32_bf16 v[28:31], v[152:155], v[200:203], v[28:31]
	v_mfma_f32_16x16x32_bf16 v[24:27], v[160:163], v[200:203], v[24:27]
	v_mfma_f32_16x16x32_bf16 v[12:15], v[152:155], v[208:211], v[12:15]
	v_mfma_f32_16x16x32_bf16 v[8:11], v[160:163], v[208:211], v[8:11]
	v_mfma_f32_16x16x32_bf16 v[60:63], v[156:159], v[188:191], v[60:63]
	v_mfma_f32_16x16x32_bf16 v[56:59], v[164:167], v[188:191], v[56:59]
	v_mfma_f32_16x16x32_bf16 v[44:47], v[156:159], v[196:199], v[44:47]
	v_mfma_f32_16x16x32_bf16 v[40:43], v[164:167], v[196:199], v[40:43]
	v_mfma_f32_16x16x32_bf16 v[28:31], v[156:159], v[204:207], v[28:31]
	v_mfma_f32_16x16x32_bf16 v[24:27], v[164:167], v[204:207], v[24:27]
	v_mfma_f32_16x16x32_bf16 v[12:15], v[156:159], v[212:215], v[12:15]
	v_mfma_f32_16x16x32_bf16 v[8:11], v[164:167], v[212:215], v[8:11]
	v_mfma_f32_16x16x32_bf16 v[52:55], v[168:171], v[184:187], v[52:55]
	v_mfma_f32_16x16x32_bf16 v[48:51], v[176:179], v[184:187], v[48:51]
	v_mfma_f32_16x16x32_bf16 v[36:39], v[168:171], v[192:195], v[36:39]
	v_mfma_f32_16x16x32_bf16 v[32:35], v[176:179], v[192:195], v[32:35]
	v_mfma_f32_16x16x32_bf16 v[20:23], v[168:171], v[200:203], v[20:23]
	v_mfma_f32_16x16x32_bf16 v[16:19], v[176:179], v[200:203], v[16:19]
	v_mfma_f32_16x16x32_bf16 v[4:7], v[168:171], v[208:211], v[4:7]
	v_mfma_f32_16x16x32_bf16 v[0:3], v[176:179], v[208:211], v[0:3]
	v_mfma_f32_16x16x32_bf16 v[52:55], v[172:175], v[188:191], v[52:55]
	v_mfma_f32_16x16x32_bf16 v[48:51], v[180:183], v[188:191], v[48:51]
	v_mfma_f32_16x16x32_bf16 v[36:39], v[172:175], v[196:199], v[36:39]
	v_mfma_f32_16x16x32_bf16 v[32:35], v[180:183], v[196:199], v[32:35]
	v_mfma_f32_16x16x32_bf16 v[20:23], v[172:175], v[204:207], v[20:23]
	v_mfma_f32_16x16x32_bf16 v[16:19], v[180:183], v[204:207], v[16:19]
	v_mfma_f32_16x16x32_bf16 v[4:7], v[172:175], v[212:215], v[4:7]
	v_mfma_f32_16x16x32_bf16 v[0:3], v[180:183], v[212:215], v[0:3]
	s_setprio 0
	s_barrier
	s_add_i32 s64, 0, 0x18000
	s_add_i32 s65, 0, 0x1c000
	v_add_u32_e32 v164, s64, v150
	v_add_u32_e32 v180, s65, v150
	ds_read_b128 v[152:155], v164
	ds_read_b128 v[156:159], v164 offset:1024
	ds_read_b128 v[160:163], v164 offset:2048
	ds_read_b128 v[164:167], v164 offset:3072
	ds_read_b128 v[168:171], v180
	ds_read_b128 v[172:175], v180 offset:1024
	ds_read_b128 v[176:179], v180 offset:2048
	ds_read_b128 v[180:183], v180 offset:3072
	s_add_u32 s36, s36, 0x80000
	s_addc_u32 s37, s37, 0
	s_mov_b32 m0, s50
	v_lshl_add_u64 v[224:225], s[36:37], 0, v[128:129]
	ds_read_b128 v[184:187], v151 offset:32768
	ds_read_b128 v[188:191], v151 offset:33792
	ds_read_b128 v[192:195], v151 offset:34816
	ds_read_b128 v[196:199], v151 offset:35840
	ds_read_b128 v[200:203], v151 offset:36864
	ds_read_b128 v[204:207], v151 offset:37888
	ds_read_b128 v[208:211], v151 offset:38912
	ds_read_b128 v[212:215], v151 offset:39936
	global_load_lds_dwordx4 v[224:225], off
	v_lshl_add_u64 v[224:225], s[36:37], 0, v[132:133]
	s_mov_b32 m0, s51
	s_nop 0
	global_load_lds_dwordx4 v[224:225], off
	s_waitcnt vmcnt(8)
	s_waitcnt lgkmcnt(0)
	s_barrier
	s_setprio 1
	v_mfma_f32_16x16x32_bf16 v[124:127], v[152:155], v[184:187], v[124:127]
	v_mfma_f32_16x16x32_bf16 v[120:123], v[160:163], v[184:187], v[120:123]
	v_mfma_f32_16x16x32_bf16 v[108:111], v[152:155], v[192:195], v[108:111]
	v_mfma_f32_16x16x32_bf16 v[104:107], v[160:163], v[192:195], v[104:107]
	v_mfma_f32_16x16x32_bf16 v[92:95], v[152:155], v[200:203], v[92:95]
	v_mfma_f32_16x16x32_bf16 v[88:91], v[160:163], v[200:203], v[88:91]
	v_mfma_f32_16x16x32_bf16 v[76:79], v[152:155], v[208:211], v[76:79]
	v_mfma_f32_16x16x32_bf16 v[72:75], v[160:163], v[208:211], v[72:75]
	v_mfma_f32_16x16x32_bf16 v[124:127], v[156:159], v[188:191], v[124:127]
	v_mfma_f32_16x16x32_bf16 v[120:123], v[164:167], v[188:191], v[120:123]
	v_mfma_f32_16x16x32_bf16 v[108:111], v[156:159], v[196:199], v[108:111]
	v_mfma_f32_16x16x32_bf16 v[104:107], v[164:167], v[196:199], v[104:107]
	v_mfma_f32_16x16x32_bf16 v[92:95], v[156:159], v[204:207], v[92:95]
	v_mfma_f32_16x16x32_bf16 v[88:91], v[164:167], v[204:207], v[88:91]
	v_mfma_f32_16x16x32_bf16 v[76:79], v[156:159], v[212:215], v[76:79]
	v_mfma_f32_16x16x32_bf16 v[72:75], v[164:167], v[212:215], v[72:75]
	v_mfma_f32_16x16x32_bf16 v[116:119], v[168:171], v[184:187], v[116:119]
	v_mfma_f32_16x16x32_bf16 v[112:115], v[176:179], v[184:187], v[112:115]
	v_mfma_f32_16x16x32_bf16 v[100:103], v[168:171], v[192:195], v[100:103]
	v_mfma_f32_16x16x32_bf16 v[96:99], v[176:179], v[192:195], v[96:99]
	v_mfma_f32_16x16x32_bf16 v[84:87], v[168:171], v[200:203], v[84:87]
	v_mfma_f32_16x16x32_bf16 v[80:83], v[176:179], v[200:203], v[80:83]
	v_mfma_f32_16x16x32_bf16 v[68:71], v[168:171], v[208:211], v[68:71]
	v_mfma_f32_16x16x32_bf16 v[64:67], v[176:179], v[208:211], v[64:67]
	v_mfma_f32_16x16x32_bf16 v[116:119], v[172:175], v[188:191], v[116:119]
	v_mfma_f32_16x16x32_bf16 v[112:115], v[180:183], v[188:191], v[112:115]
	v_mfma_f32_16x16x32_bf16 v[100:103], v[172:175], v[196:199], v[100:103]
	v_mfma_f32_16x16x32_bf16 v[96:99], v[180:183], v[196:199], v[96:99]
	v_mfma_f32_16x16x32_bf16 v[84:87], v[172:175], v[204:207], v[84:87]
	v_mfma_f32_16x16x32_bf16 v[80:83], v[180:183], v[204:207], v[80:83]
	v_mfma_f32_16x16x32_bf16 v[68:71], v[172:175], v[212:215], v[68:71]
	v_mfma_f32_16x16x32_bf16 v[64:67], v[180:183], v[212:215], v[64:67]
	s_setprio 0
	s_barrier
	s_add_i32 s36, s64, s47
	v_lshl_add_u64 v[216:217], v[216:217], 0, s[18:19]
	s_mov_b32 m0, s36
	ds_read_b128 v[184:187], v151 offset:49152
	ds_read_b128 v[188:191], v151 offset:50176
	ds_read_b128 v[192:195], v151 offset:51200
	ds_read_b128 v[196:199], v151 offset:52224
	ds_read_b128 v[200:203], v151 offset:53248
	ds_read_b128 v[204:207], v151 offset:54272
	ds_read_b128 v[208:211], v151 offset:55296
	ds_read_b128 v[212:215], v151 offset:56320
	global_load_lds_dwordx4 v[216:217], off
	s_add_i32 m0, s36, 0x2000
	s_add_u32 s34, s34, 0x80080
	v_lshl_add_u64 v[216:217], v[218:219], 0, s[18:19]
	s_addc_u32 s35, s35, 0
	s_add_i32 s36, s65, s47
	global_load_lds_dwordx4 v[216:217], off
	v_lshl_add_u64 v[216:217], s[34:35], 0, v[130:131]
	s_mov_b32 m0, s36
	s_nop 0
	global_load_lds_dwordx4 v[216:217], off
	v_lshl_add_u64 v[216:217], s[34:35], 0, v[134:135]
	s_add_i32 m0, s36, 0x2000
	s_nop 0
	global_load_lds_dwordx4 v[216:217], off
	v_lshl_add_u64 v[216:217], v[220:221], 0, s[18:19]
	s_mov_b32 m0, s54
	s_nop 0
	global_load_lds_dwordx4 v[216:217], off
	v_lshl_add_u64 v[216:217], v[222:223], 0, s[18:19]
	s_mov_b32 m0, s55
	s_nop 0
	global_load_lds_dwordx4 v[216:217], off
	s_waitcnt vmcnt(8)
	s_waitcnt lgkmcnt(0)
	s_barrier
	s_setprio 1
	v_mfma_f32_16x16x32_bf16 v[60:63], v[152:155], v[184:187], v[60:63]
	v_mfma_f32_16x16x32_bf16 v[56:59], v[160:163], v[184:187], v[56:59]
	v_mfma_f32_16x16x32_bf16 v[44:47], v[152:155], v[192:195], v[44:47]
	v_mfma_f32_16x16x32_bf16 v[40:43], v[160:163], v[192:195], v[40:43]
	v_mfma_f32_16x16x32_bf16 v[28:31], v[152:155], v[200:203], v[28:31]
	v_mfma_f32_16x16x32_bf16 v[24:27], v[160:163], v[200:203], v[24:27]
	v_mfma_f32_16x16x32_bf16 v[12:15], v[152:155], v[208:211], v[12:15]
	v_mfma_f32_16x16x32_bf16 v[8:11], v[160:163], v[208:211], v[8:11]
	v_mfma_f32_16x16x32_bf16 v[60:63], v[156:159], v[188:191], v[60:63]
	v_mfma_f32_16x16x32_bf16 v[56:59], v[164:167], v[188:191], v[56:59]
	v_mfma_f32_16x16x32_bf16 v[44:47], v[156:159], v[196:199], v[44:47]
	v_mfma_f32_16x16x32_bf16 v[40:43], v[164:167], v[196:199], v[40:43]
	v_mfma_f32_16x16x32_bf16 v[28:31], v[156:159], v[204:207], v[28:31]
	v_mfma_f32_16x16x32_bf16 v[24:27], v[164:167], v[204:207], v[24:27]
	v_mfma_f32_16x16x32_bf16 v[12:15], v[156:159], v[212:215], v[12:15]
	v_mfma_f32_16x16x32_bf16 v[8:11], v[164:167], v[212:215], v[8:11]
	v_mfma_f32_16x16x32_bf16 v[52:55], v[168:171], v[184:187], v[52:55]
	v_mfma_f32_16x16x32_bf16 v[48:51], v[176:179], v[184:187], v[48:51]
	v_mfma_f32_16x16x32_bf16 v[36:39], v[168:171], v[192:195], v[36:39]
	v_mfma_f32_16x16x32_bf16 v[32:35], v[176:179], v[192:195], v[32:35]
	v_mfma_f32_16x16x32_bf16 v[20:23], v[168:171], v[200:203], v[20:23]
	v_mfma_f32_16x16x32_bf16 v[16:19], v[176:179], v[200:203], v[16:19]
	v_mfma_f32_16x16x32_bf16 v[4:7], v[168:171], v[208:211], v[4:7]
	v_mfma_f32_16x16x32_bf16 v[0:3], v[176:179], v[208:211], v[0:3]
	v_mfma_f32_16x16x32_bf16 v[52:55], v[172:175], v[188:191], v[52:55]
	v_mfma_f32_16x16x32_bf16 v[48:51], v[180:183], v[188:191], v[48:51]
	v_mfma_f32_16x16x32_bf16 v[36:39], v[172:175], v[196:199], v[36:39]
	v_mfma_f32_16x16x32_bf16 v[32:35], v[180:183], v[196:199], v[32:35]
	v_mfma_f32_16x16x32_bf16 v[20:23], v[172:175], v[204:207], v[20:23]
	v_mfma_f32_16x16x32_bf16 v[16:19], v[180:183], v[204:207], v[16:19]
	v_mfma_f32_16x16x32_bf16 v[4:7], v[172:175], v[212:215], v[4:7]
	v_mfma_f32_16x16x32_bf16 v[0:3], v[180:183], v[212:215], v[0:3]
	s_setprio 0
	s_barrier
	s_add_i32 s63, s63, 2
	s_add_u32 s30, s30, 0x100
	s_addc_u32 s31, s31, 0
	s_cmp_gt_u32 s63, 29
	s_cbranch_scc0 .LBB0_1227
	s_add_u32 s30, s59, 0xffffff00
	s_addc_u32 s31, s60, -1
	s_andn2_b64 vcc, exec, s[4:5]
	s_cbranch_vccnz .LBB0_1230
	v_mov_b32_e32 v0, 0
	s_mov_b32 s15, s20
	s_mov_b32 s14, s22
	s_mov_b64 s[16:17], s[26:27]
	s_mov_b32 s53, s58
	v_mov_b32_e32 v1, v0
	v_pk_mov_b32 v[2:3], 0, 0
	v_pk_mov_b32 v[4:5], 0, 0
	v_pk_mov_b32 v[6:7], 0, 0
	v_pk_mov_b32 v[16:17], 0, 0
	v_pk_mov_b32 v[18:19], 0, 0
	v_pk_mov_b32 v[20:21], 0, 0
	v_pk_mov_b32 v[22:23], 0, 0
	v_pk_mov_b32 v[32:33], 0, 0
	v_pk_mov_b32 v[34:35], 0, 0
	v_pk_mov_b32 v[36:37], 0, 0
	v_pk_mov_b32 v[38:39], 0, 0
	v_pk_mov_b32 v[48:49], 0, 0
	v_pk_mov_b32 v[50:51], 0, 0
	v_pk_mov_b32 v[52:53], 0, 0
	v_pk_mov_b32 v[54:55], 0, 0
	v_pk_mov_b32 v[8:9], 0, 0
	v_pk_mov_b32 v[10:11], 0, 0
	v_pk_mov_b32 v[12:13], 0, 0
	v_pk_mov_b32 v[14:15], 0, 0
	v_pk_mov_b32 v[24:25], 0, 0
	v_pk_mov_b32 v[26:27], 0, 0
	v_pk_mov_b32 v[28:29], 0, 0
	v_pk_mov_b32 v[30:31], 0, 0
	v_pk_mov_b32 v[40:41], 0, 0
	v_pk_mov_b32 v[42:43], 0, 0
	v_pk_mov_b32 v[44:45], 0, 0
	v_pk_mov_b32 v[46:47], 0, 0
	v_pk_mov_b32 v[56:57], 0, 0
	v_pk_mov_b32 v[58:59], 0, 0
	v_pk_mov_b32 v[60:61], 0, 0
	v_pk_mov_b32 v[62:63], 0, 0
	v_pk_mov_b32 v[64:65], 0, 0
	v_pk_mov_b32 v[66:67], 0, 0
	v_pk_mov_b32 v[68:69], 0, 0
	v_pk_mov_b32 v[70:71], 0, 0
	v_pk_mov_b32 v[80:81], 0, 0
	v_pk_mov_b32 v[82:83], 0, 0
	v_pk_mov_b32 v[84:85], 0, 0
	v_pk_mov_b32 v[86:87], 0, 0
	v_pk_mov_b32 v[96:97], 0, 0
	v_pk_mov_b32 v[98:99], 0, 0
	v_pk_mov_b32 v[100:101], 0, 0
	v_pk_mov_b32 v[102:103], 0, 0
	v_pk_mov_b32 v[112:113], 0, 0
	v_pk_mov_b32 v[114:115], 0, 0
	v_pk_mov_b32 v[116:117], 0, 0
	v_pk_mov_b32 v[118:119], 0, 0
	v_pk_mov_b32 v[72:73], 0, 0
	v_pk_mov_b32 v[74:75], 0, 0
	v_pk_mov_b32 v[76:77], 0, 0
	v_pk_mov_b32 v[78:79], 0, 0
	v_pk_mov_b32 v[88:89], 0, 0
	v_pk_mov_b32 v[90:91], 0, 0
	v_pk_mov_b32 v[92:93], 0, 0
	v_pk_mov_b32 v[94:95], 0, 0
	v_pk_mov_b32 v[104:105], 0, 0
	v_pk_mov_b32 v[106:107], 0, 0
	v_pk_mov_b32 v[108:109], 0, 0
	v_pk_mov_b32 v[110:111], 0, 0
	v_pk_mov_b32 v[120:121], 0, 0
	v_pk_mov_b32 v[122:123], 0, 0
	v_pk_mov_b32 v[124:125], 0, 0
	v_pk_mov_b32 v[126:127], 0, 0
	s_andn2_b64 vcc, exec, s[0:1]
	s_cbranch_vccnz .LBB0_1231
	s_branch .LBB0_1232
